# workgroup ids permuted so that the eight workgroups working on one 256-row block in the FFN chain (norm, FFN-in, FFN-out, mixer-in, mixer-out) all run on the same XCD
# speedup vs baseline: 1.0099x; 1.0099x over previous
_Z10fwd_kernel6Params:
	s_lshr_b32 s28, s2, 3
	s_bfe_u32 s29, s28, 0x10002
	s_and_b32 s10, s28, 3
	s_lshl_b32 s10, s10, 1
	s_or_b32 s29, s29, s10
	s_and_b32 s10, s2, 7
	s_lshl_b32 s10, s10, 3
	s_or_b32 s29, s29, s10
	s_lshr_b32 s10, s28, 3
	s_lshl_b32 s10, s10, 6
	s_or_b32 s2, s29, s10
	s_add_u32 s10, s0, 0xa0
	v_writelane_b32 v255, s2, 0
	s_load_dwordx2 s[28:29], s[0:1], 0xa0
	s_load_dword s2, s[0:1], 0xa8
	s_addc_u32 s11, s1, 0
	v_and_b32_e32 v147, 0x3ff, v0
	v_cmp_eq_u32_e32 vcc, 0, v147
	s_and_saveexec_b64 s[4:5], vcc
	s_cbranch_execz .LBB0_3
	s_add_i32 s3, 0, 0x23f00
	v_mov_b32_e32 v1, 0
	v_mov_b32_e32 v2, s3
	s_add_i32 s3, 0, 0x23f04
	s_mov_b64 s[6:7], exec
	ds_write_b32 v2, v1
	v_mov_b32_e32 v2, s3
	ds_write_b32 v2, v1
	v_mbcnt_lo_u32_b32 v1, s6, 0
	v_mbcnt_hi_u32_b32 v1, s7, v1
	v_cmp_eq_u32_e32 vcc, 0, v1
	s_getreg_b32 s3, hwreg(HW_REG_XCC_ID, 0, 4)
	s_and_b64 s[8:9], exec, vcc
	s_mov_b64 exec, s[8:9]
	s_cbranch_execz .LBB0_3
	s_load_dwordx2 s[8:9], s[0:1], 0x98
	s_lshl_b32 s3, s3, 8
	s_and_b32 s3, s3, 0xf00
	v_mov_b32_e32 v1, 0x4000
	s_waitcnt lgkmcnt(0)
	s_add_u32 s8, s8, s3
	s_addc_u32 s9, s9, 0
	s_bcnt1_i32_b64 s3, s[6:7]
	v_mov_b32_e32 v2, s3
	global_atomic_add v1, v2, s[8:9] offset:1024
